# MLA attention phase: static s_setprio 1 for workgroups with blockIdx bit 8 set (one of the two co-resident blocks per CU)
# baseline (speedup 1.0000x reference)
; DI float fexp2(float x) { return __builtin_amdgcn_exp2f(x); }
; DI int otid() { int t = threadIdx.x; asm volatile("" : "+v"(t)); return t; }
; DI unsigned xb_xcc_id() { return (unsigned)__builtin_amdgcn_s_getreg((3 << 11) | 20) & 0xFu; }
;   constexpr int DQK = (MODE == 1) ? 96 : 64, NKS = DQK / 16, KST = DQK + 8;
;   constexpr int KCH = (MODE == 1) ? 3 : 2;
;   const int t = otid(), lane = t & 63, w = t >> 6, r = lane & 31, hh = lane >> 5;
;   bf16_t* Kl = smem;
;   bf16_t* Vl = smem + 2 * 64 * KST;
;   float* Fl = (float*)(Vl + 2 * 64 * VST);
;   int* s_item = (int*)(Fl + 128);
;   int* s_flag = s_item + 4;
;   const int total = NB * NH * 65;
;   const int lkey = t >> 2, lsub = t & 3;
;   constexpr float LOG2E = 1.44269504f;
;   const float c2 = (MODE == 1 ? 0.10206207f : 0.125f) * LOG2E;
;   const int myx = (int)(xb_xcc_id() & 7u);
;   int qx = 0;
;   for (;;) {
;     __syncthreads();
;     if (t == 0) {
;       int v = -1;
;       while (qx < 8) {
;         const int xx = (myx + qx) & 7;
;         const int got = (int)atomicAdd(aa.ctr + xx, 1u);
;         if (got < total / 8) { v = got * 8 + xx; break; }
;         ++qx;
;       }
;       s_item[0] = v; s_item[1] = qx;
;     }
;     __syncthreads();
;     const int enc = s_item[0]; qx = s_item[1];
;     if (enc < 0) break;
;     const int xx_ = enc & 7, idx = enc >> 3;
;     const int qt = 64 - idx % 65, bh = (idx / 65) * 8 + xx_, b = bh >> 4, hd = bh & 15;
;     const int q0 = qt * 128;
;     const int posq = q0 + w * 32 + r;
;     const bool qvalid = posq < L;
;     const int pq = qvalid ? posq : L - 1;
;     bf16_t* qptr = aa.q + (size_t)(b * L + pq) * aa.ldq + hd * aa.hs;
;     bf16x8 qf[NKS];
; #pragma unroll
;     for (int ks = 0; ks < NKS; ++ks) qf[ks] = *(const bf16x8*)(qptr + ks * 16 + 8 * hh);
;     if (MODE == 1) {
; #pragma unroll
;       for (int j = 0; j < 8; j += 2) {
;         float o1[2], o2[2];
; #pragma unroll
;         for (int e = 0; e < 2; ++e) {
;           const int i = 8 * hh + j + e;
;           const float inv = fexp2(-(float)i * 0.83048202f);
;           const float ang = (float)pq * inv;
;           const float n = rintf(ang * 0.15915494f);
;           float rr = fmaf(-n, 6.2831855f, ang); rr = fmaf(-n, -1.7484555e-7f, rr);
.LBB0_814:
	s_andn2_b64 vcc, exec, s[4:5]
	s_cbranch_vccnz .LBB0_910
	v_mov_b32_e32 v1, v172
	s_movk_i32 s1, 0xd0
	v_and_b32_e32 v150, 31, v1
	v_bfe_u32 v3, v1, 5, 1
	s_waitcnt vmcnt(0)
	v_ashrrev_i32_e32 v187, 2, v1
	v_cmp_eq_u32_e64 s[42:43], 0, v1
	v_ashrrev_i32_e32 v0, 1, v1
	v_lshlrev_b32_e32 v1, 3, v1
	v_and_b32_e32 v2, 24, v1
	v_lshlrev_b32_e32 v144, 1, v2
	v_mad_u64_u32 v[152:153], s[4:5], v187, s1, v[144:145]
	s_movk_i32 s1, 0xffb8
	v_mul_u32_u24_e32 v1, 0x68, v150
	v_and_b32_e32 v188, 0xffffffe0, v0
	v_lshlrev_b32_e32 v0, 3, v3
	v_mad_u64_u32 v[154:155], s[4:5], v187, s1, v[152:153]
	v_lshlrev_b32_e32 v1, 1, v1
	v_mul_i32_i24_e32 v5, 0xffffffb8, v150
	v_lshl_add_u32 v153, v3, 4, v1
	v_add3_u32 v155, v1, v5, v0
	v_cvt_f32_ubyte0_e32 v1, v0
	v_mul_f32_e32 v1, 0xbf549a78, v1
	v_exp_f32_e32 v189, v1
	v_or_b32_e32 v1, 1, v0
	v_cvt_f32_ubyte0_e32 v1, v1
	v_mul_f32_e32 v1, 0xbf549a78, v1
	v_exp_f32_e32 v190, v1
	v_or_b32_e32 v1, 2, v0
	v_cvt_f32_ubyte0_e32 v1, v1
	v_mul_f32_e32 v1, 0xbf549a78, v1
	v_exp_f32_e32 v191, v1
	v_or_b32_e32 v1, 3, v0
	v_cvt_f32_ubyte0_e32 v1, v1
	v_mul_f32_e32 v1, 0xbf549a78, v1
	v_exp_f32_e32 v192, v1
	v_or_b32_e32 v1, 4, v0
	v_cvt_f32_ubyte0_e32 v1, v1
	v_mul_f32_e32 v1, 0xbf549a78, v1
	v_exp_f32_e32 v193, v1
	v_or_b32_e32 v1, 5, v0
	v_cvt_f32_ubyte0_e32 v1, v1
	v_mul_f32_e32 v1, 0xbf549a78, v1
	v_exp_f32_e32 v194, v1
	v_or_b32_e32 v1, 6, v0
	v_cvt_f32_ubyte0_e32 v1, v1
	v_mul_f32_e32 v1, 0xbf549a78, v1
	v_exp_f32_e32 v195, v1
	v_or_b32_e32 v1, 7, v0
	v_cvt_f32_ubyte0_e32 v1, v1
	v_mul_f32_e32 v1, 0xbf549a78, v1
	v_exp_f32_e32 v196, v1
	v_readlane_b32 s4, v228, 6
	v_readlane_b32 s24, v228, 4
	v_lshlrev_b32_e32 v4, 2, v3
	v_readlane_b32 s5, v228, 7
	v_readlane_b32 s25, v228, 5
	v_mad_i32_i24 v1, v3, -4, v188
	s_movk_i32 s1, 0x2040
	s_getreg_b32 s14, hwreg(HW_REG_XCC_ID, 0, 4)
	s_mov_b32 s15, 0
	v_lshl_add_u64 v[156:157], s[4:5], 0, v[144:145]
	v_lshl_add_u64 v[158:159], s[64:65], 0, v[144:145]
	v_lshl_add_u64 v[160:161], s[24:25], 0, v[144:145]
	v_add3_u32 v197, v1, v150, s1
	v_lshlrev_b32_e32 v144, 1, v0
	v_lshlrev_b32_e32 v162, 1, v2
	v_lshlrev_b32_e32 v164, 1, v4
	v_readlane_b32 s100, v229, 2
	s_and_b32 s100, s100, 0x100
	s_cmp_lg_u32 s100, 0
	s_cbranch_scc0 .Lmla_noprio
	s_setprio 1
.Lmla_noprio:
	s_branch .LBB0_817
.LBB0_816:
	s_or_b64 exec, exec, s[4:5]

;     ...
;   for (;;) {
;     __syncthreads();
;     if (t == 0) {
;       int v = -1;
;       while (qx < 8) {
;         const int xx = (myx + qx) & 7;
;         const int got = (int)atomicAdd(aa.ctr + xx, 1u);
;         if (got < total / 8) { v = got * 8 + xx; break; }
;         ++qx;
;       }
;       s_item[0] = v; s_item[1] = qx;
;     }
;     __syncthreads();
;     const int enc = s_item[0]; qx = s_item[1];
;     if (enc < 0) break;
.LBB0_859:
	s_cbranch_execz .LBB0_817
	s_setprio 0
	v_readlane_b32 s4, v229, 3
	v_readlane_b32 s5, v229, 4
	s_load_dwordx4 s[40:43], s[4:5], 0xa00
	v_readlane_b32 s1, v228, 43
	s_add_i32 s1, s1, 3
	s_waitcnt lgkmcnt(0)
	s_cmp_ge_i32 s1, s41
	s_cbranch_scc1 .LBB0_910
	s_waitcnt vmcnt(0)
	s_barrier
	s_mov_b64 s[4:5], exec
	v_readlane_b32 s6, v229, 0
	v_readlane_b32 s7, v229, 1
	s_and_b64 s[6:7], s[4:5], s[6:7]
	s_mov_b64 exec, s[6:7]
	s_cbranch_execz .LBB0_909
	s_waitcnt vmcnt(0) expcnt(0) lgkmcnt(0)
	ds_read_b32 v2, v177
	ds_read_b32 v0, v178
	s_waitcnt lgkmcnt(1)
	v_cmp_ne_u32_e32 vcc, 0, v2
	s_cbranch_vccnz .LBB0_877
	s_mov_b32 s12, 1
	s_branch .LBB0_865
